# GLU to attention seam without a grid wait: write-through row sums + arrival counter, waited in the first attention epilogue
# baseline (speedup 1.0000x reference)
; #define LAS __attribute__((address_space(3)))
; #define GSYNC() do { XcdBarrier xb_; xb_.bar = (unsigned*)(KARGS()->ws + WS_CTL) + 1024; xb_.x = xb_xcc_id(); xb_.st = (volatile LAS unsigned*)(lds + LDS_XB); xcd_barrier(xb_); } while (0)
; __global__ void __launch_bounds__(512, 2) fwd_kernel(Args a) {
;     ...
;     grid.sync();
;     ...
;     for (int l = 0; l < DEPTH; ++l) {
;         if (PROBE == 4) { for (int rep = 0; rep < 10; ++rep) GSYNC(); }
;         for (int rep = 0; rep < (PROBE == 2 ? 2 : 1); ++rep)
;         { PH StdSched S; S.init(T, 2 * FF, G, bid, D, D); EpiFfnUp E{(bf16_t*)(ar + AR_HID), ssb + (size_t)(4 * l + 0) * T * 16, (const LAS float*)(lds + LDS_RS)};
.LBB0_489:
	s_or_b64 exec, exec, s[6:7]
	s_barrier
	s_load_dwordx2 s[8:9], s[0:1], 0x128
	s_load_dword s10, s[0:1], 0x130
	v_mov_b32_e32 v2, 0x6100
	s_mov_b32 s11, 0
	s_waitcnt lgkmcnt(0)
	global_load_dwordx4 v[0:3], v2, s[8:9] offset:0 sc1
	s_waitcnt vmcnt(0)
	v_readfirstlane_b32 s12, v0
	s_nop 1
	s_add_i32 s13, s12, -1
	s_and_b32 s13, s13, s12
	s_or_b32 s11, s11, s13
	s_cmp_eq_u32 s12, 0
	s_cselect_b32 s13, 1, 0
	s_or_b32 s11, s11, s13
	v_readfirstlane_b32 s12, v1
	s_nop 1
	s_add_i32 s13, s12, -1
	s_and_b32 s13, s13, s12
	s_or_b32 s11, s11, s13
	s_cmp_eq_u32 s12, 0
	s_cselect_b32 s13, 1, 0
	s_or_b32 s11, s11, s13
	v_readfirstlane_b32 s12, v2
	s_nop 1
	s_add_i32 s13, s12, -1
	s_and_b32 s13, s13, s12
	s_or_b32 s11, s11, s13
	s_cmp_eq_u32 s12, 0
	s_cselect_b32 s13, 1, 0
	s_or_b32 s11, s11, s13
	v_readfirstlane_b32 s12, v3
	s_nop 1
	s_add_i32 s13, s12, -1
	s_and_b32 s13, s13, s12
	s_or_b32 s11, s11, s13
	s_cmp_eq_u32 s12, 0
	s_cselect_b32 s13, 1, 0
	s_or_b32 s11, s11, s13
	v_mov_b32_e32 v2, 0x6100
	global_load_dwordx4 v[0:3], v2, s[8:9] offset:16 sc1
	s_waitcnt vmcnt(0)
	v_readfirstlane_b32 s12, v0
	s_nop 1
	s_add_i32 s13, s12, -1
	s_and_b32 s13, s13, s12
	s_or_b32 s11, s11, s13
	s_cmp_eq_u32 s12, 0
	s_cselect_b32 s13, 1, 0
	s_or_b32 s11, s11, s13
	v_readfirstlane_b32 s12, v1
	s_nop 1
	s_add_i32 s13, s12, -1
	s_and_b32 s13, s13, s12
	s_or_b32 s11, s11, s13
	s_cmp_eq_u32 s12, 0
	s_cselect_b32 s13, 1, 0
	s_or_b32 s11, s11, s13
	v_readfirstlane_b32 s12, v2
	s_nop 1
	s_add_i32 s13, s12, -1
	s_and_b32 s13, s13, s12
	s_or_b32 s11, s11, s13
	s_cmp_eq_u32 s12, 0
	s_cselect_b32 s13, 1, 0
	s_or_b32 s11, s11, s13
	v_readfirstlane_b32 s12, v3
	s_nop 1
	s_add_i32 s13, s12, -1
	s_and_b32 s13, s13, s12
	s_or_b32 s11, s11, s13
	s_cmp_eq_u32 s12, 0
	s_cselect_b32 s13, 1, 0
	s_or_b32 s11, s11, s13
	s_xor_b32 s10, s10, 0x100
	s_or_b32 s11, s11, s10
	s_cmp_eq_u32 s11, 0
	s_cselect_b32 s11, 1, 0
	s_mov_b32 s12, 0
	v_writelane_b32 v255, s11, 40
	v_writelane_b32 v255, s12, 41
	v_writelane_b32 v255, s12, 43
	s_load_dword s2, s[0:1], 0x138
	s_cmpk_gt_i32 s34, 0x7f
	s_cselect_b64 s[4:5], -1, 0
	s_mul_i32 s3, s95, s94
	v_writelane_b32 v255, s4, 2
	s_waitcnt lgkmcnt(0)
	s_mul_i32 s3, s3, s2
	s_add_i32 s2, 0, 0x22100
	v_writelane_b32 v255, s5, 3
	v_writelane_b32 v255, s2, 4
	s_add_i32 s2, 0, 0x22000
	s_mov_b32 s19, 0
	v_writelane_b32 v255, s2, 5
	s_add_i32 s2, 0, 0x22004
	s_mov_b64 s[50:51], -1
	s_movk_i32 s95, 0xb00
	v_mov_b32_e32 v219, 0x358637bd
	s_mov_b32 s85, 0x800000
	s_mov_b32 s86, 0x1fffe0
	v_mov_b32_e32 v1, 0
	s_movk_i32 s89, 0x3c0
	s_mov_b64 s[26:27], 0x80
	s_mov_b64 s[28:29], 0x100
	s_movk_i32 s90, 0x1600
	v_writelane_b32 v255, s2, 7
	v_mov_b32_e32 v254, 1
	s_movk_i32 s96, 0x1700
	s_movk_i32 s97, 0x500
	s_movk_i32 s20, 0x1f00
	s_movk_i32 s23, 0x280
	s_movk_i32 s34, 0x70
	s_add_i32 s41, 0, 0x18200
	s_movk_i32 s36, 0xffdf
	s_mov_b32 s37, 0xff800000
	s_mov_b32 s84, 0x41200000
	v_mov_b32_e32 v218, 0x260
	s_add_i32 s35, 0, 0x21000
	v_mov_b64_e32 v[224:225], 0xb00
	v_mov_b64_e32 v[192:193], 0xaff
	v_mov_b64_e32 v[194:195], 0x200
	v_mov_b64_e32 v[234:235], 0x1ff
	v_mov_b32_e32 v229, 0x80
	v_mov_b32_e32 v230, 0xff800000
	s_mov_b32 s30, 0xbfb8aa3b
	s_mov_b32 s38, 0x3d372713
	s_mov_b32 s40, 0xc0135761
	s_mov_b64 s[42:43], 0x180
	s_mov_b32 s48, s19
	s_branch .LBB0_493

; __device__ __forceinline__ u32x4 pack8(f32x4 a, f32x4 b) { u32x4 w; w.x = cvtpk(a[0], a[1]); w.y = cvtpk(a[2], a[3]); w.z = cvtpk(b[0], b[1]); w.w = cvtpk(b[2], b[3]); return w; }
; __device__ __forceinline__ float fast_exp2(float x) { return __builtin_amdgcn_exp2f(x); }
; __device__ __forceinline__ float fast_rcp(float x) { return __builtin_amdgcn_rcpf(x); }
;     __device__ __forceinline__ void operator()(AccRef acc, const Unit& u, int wr, int wc, int fr, int fq) const {
;         const int c0 = u.pn * 128 + wc * 32 + 8 * fq;
;         const f32x4 bv0 = *(const f32x4*)(bglu + c0), bv1 = *(const f32x4*)(bglu + c0 + 4), bg0 = *(const f32x4*)(bglu + 512 + c0), bg1 = *(const f32x4*)(bglu + 512 + c0 + 4);
; #pragma unroll
;         for (int ai = 0; ai < 2; ++ai)
; #pragma unroll
;             for (int m = 0; m < 4; ++m) {
;                 const int row = u.pm * 256 + ai * 128 + wr * 64 + m * 16 + fr;
;                 f32x4 o0, o1; float part = 0.f;
;                 {
;                     f32x4 g0 = (acc[ai][1][m][0] + bg0) * (-LOG2E), g1 = (acc[ai][1][m][1] + bg1) * (-LOG2E);
; #pragma unroll
;                     for (int j = 0; j < 4; ++j) { g0[j] = fast_exp2(g0[j]); g1[j] = fast_exp2(g1[j]); }
;                     g0 = g0 + 1.0f; g1 = g1 + 1.0f;
; #pragma unroll
;                     for (int j = 0; j < 4; ++j) { g0[j] = fast_rcp(g0[j]); g1[j] = fast_rcp(g1[j]); }
;                     o0 = (acc[ai][0][m][0] + bv0) * g0; o1 = (acc[ai][0][m][1] + bv1) * g1;
;                     const f32x4 sq = o0 * o0 + o1 * o1; part += (sq[0] + sq[1]) + (sq[2] + sq[3]);
;                 }
;                 *(u32x4*)(mix + (size_t)row * D + c0) = pack8(o0, o1);
;                 part = fq_sum(part);
;                 if (fq == 0) ssq[(size_t)row * 16 + u.pn * 4 + wc] = part;
;             }
.LBB0_1257:
	v_mov_b32_e32 v0, v236
	s_lshl_b32 s25, s31, 7
	v_bfe_u32 v149, v0, 4, 2
	v_lshl_or_b32 v114, v149, 3, s25
	v_or_b32_e32 v146, s65, v114
	v_ashrrev_i32_e32 v147, 31, v146
	v_lshl_add_u64 v[126:127], v[146:147], 2, s[12:13]
	global_load_dwordx4 v[114:117], v[126:127], off offset:16
	global_load_dwordx4 v[118:121], v[126:127], off
	global_load_dwordx4 v[122:125], v[126:127], off offset:2064
	s_nop 0
	global_load_dwordx4 v[126:129], v[126:127], off offset:2048
	s_lshl_b32 s25, s75, 8
	s_add_i32 s25, s25, s47
	v_and_or_b32 v148, v0, 15, s25
	v_cmp_eq_u32_e32 vcc, 0, v149
	v_ashrrev_i32_e32 v149, 31, v148
	s_lshl_b32 s58, s31, 2
	s_ashr_i32 s59, s58, 31
	s_waitcnt vmcnt(0)
	v_pk_add_f32 v[136:137], v[136:137], v[116:117]
	v_pk_add_f32 v[134:135], v[134:135], v[114:115]
	v_pk_add_f32 v[132:133], v[132:133], v[124:125]
	v_pk_add_f32 v[130:131], v[130:131], v[122:123]
	v_pk_add_f32 v[138:139], v[138:139], v[126:127]
	v_pk_mul_f32 v[132:133], v[132:133], s[30:31] op_sel_hi:[1,0]
	v_pk_mul_f32 v[130:131], v[130:131], s[30:31] op_sel_hi:[1,0]
	v_pk_add_f32 v[140:141], v[140:141], v[128:129]
	v_pk_mul_f32 v[138:139], v[138:139], s[30:31] op_sel_hi:[1,0]
	v_exp_f32_e32 v130, v130
	v_exp_f32_e32 v131, v131
	v_exp_f32_e32 v132, v132
	v_exp_f32_e32 v133, v133
	v_pk_mul_f32 v[140:141], v[140:141], s[30:31] op_sel_hi:[1,0]
	v_exp_f32_e32 v138, v138
	v_exp_f32_e32 v139, v139
	v_exp_f32_e32 v140, v140
	v_exp_f32_e32 v141, v141
	v_pk_add_f32 v[132:133], v[132:133], 1.0 op_sel_hi:[1,0]
	v_pk_add_f32 v[130:131], v[130:131], 1.0 op_sel_hi:[1,0]
	v_pk_add_f32 v[138:139], v[138:139], 1.0 op_sel_hi:[1,0]
	v_rcp_f32_e32 v130, v130
	v_rcp_f32_e32 v131, v131
	v_rcp_f32_e32 v132, v132
	v_rcp_f32_e32 v133, v133
	v_pk_add_f32 v[140:141], v[140:141], 1.0 op_sel_hi:[1,0]
	v_rcp_f32_e32 v138, v138
	v_rcp_f32_e32 v139, v139
	v_rcp_f32_e32 v140, v140
	v_rcp_f32_e32 v141, v141
	v_pk_add_f32 v[142:143], v[142:143], v[118:119]
	v_pk_mul_f32 v[136:137], v[136:137], v[132:133]
	v_pk_mul_f32 v[132:133], v[134:135], v[130:131]
	v_pk_add_f32 v[144:145], v[144:145], v[120:121]
	v_pk_mul_f32 v[138:139], v[142:143], v[138:139]
	v_pk_mul_f32 v[134:135], v[132:133], v[132:133]
	v_pk_mul_f32 v[140:141], v[144:145], v[140:141]
	v_pk_mul_f32 v[130:131], v[136:137], v[136:137]
	v_pk_fma_f32 v[134:135], v[138:139], v[138:139], v[134:135]
	v_pk_fma_f32 v[130:131], v[140:141], v[140:141], v[130:131]
	v_add_f32_e32 v0, v134, v135
	v_lshlrev_b64 v[134:135], 11, v[148:149]
	v_add_f32_e32 v130, v130, v131
	v_lshl_add_u64 v[134:135], s[10:11], 0, v[134:135]
	v_add_f32_e32 v0, v0, v130
	v_cvt_pk_bf16_f32 v130, v138, v139
	v_cvt_pk_bf16_f32 v131, v140, v141
	v_cvt_pk_bf16_f32 v132, v132, v133
	v_cvt_pk_bf16_f32 v133, v136, v137
	v_lshl_add_u64 v[134:135], v[146:147], 1, v[134:135]
	global_store_dwordx4 v[134:135], v[130:133], off
	s_nop 1
	v_mov_b32_e32 v130, v0
	s_nop 1
	v_permlane32_swap_b32_e32 v0, v130
	v_add_f32_e32 v0, v0, v130
	v_mov_b32_e32 v130, v0
	s_nop 1
	v_permlane16_swap_b32_e32 v0, v130
	s_and_saveexec_b64 s[60:61], vcc
	s_cbranch_execz .LBB0_1259
	v_lshlrev_b64 v[132:133], 6, v[148:149]
	v_lshl_add_u64 v[132:133], s[14:15], 0, v[132:133]
	v_lshl_add_u64 v[132:133], s[58:59], 2, v[132:133]
	s_lshl_b32 s62, s46, 2
	s_mov_b32 s63, s19
	v_lshl_add_u64 v[132:133], v[132:133], 0, s[62:63]
	v_add_f32_e32 v0, v0, v130
	global_store_dword v[132:133], v0, off sc0 sc1
.LBB0_1259:
	s_or_b64 exec, exec, s[60:61]
	v_pk_add_f32 v[108:109], v[108:109], v[124:125]
	v_pk_add_f32 v[106:107], v[106:107], v[122:123]
	v_pk_add_f32 v[112:113], v[112:113], v[128:129]
	v_pk_add_f32 v[110:111], v[110:111], v[126:127]
	v_pk_mul_f32 v[108:109], v[108:109], s[30:31] op_sel_hi:[1,0]
	v_pk_mul_f32 v[106:107], v[106:107], s[30:31] op_sel_hi:[1,0]
	v_pk_mul_f32 v[112:113], v[112:113], s[30:31] op_sel_hi:[1,0]
	v_pk_mul_f32 v[110:111], v[110:111], s[30:31] op_sel_hi:[1,0]
	v_exp_f32_e32 v106, v106
	v_exp_f32_e32 v108, v108
	v_exp_f32_e32 v109, v109
	v_exp_f32_e32 v107, v107
	v_exp_f32_e32 v110, v110
	v_exp_f32_e32 v111, v111
	v_exp_f32_e32 v112, v112
	v_exp_f32_e32 v113, v113
	v_pk_add_f32 v[108:109], v[108:109], 1.0 op_sel_hi:[1,0]
	v_pk_add_f32 v[106:107], v[106:107], 1.0 op_sel_hi:[1,0]
	v_pk_add_f32 v[110:111], v[110:111], 1.0 op_sel_hi:[1,0]
	v_pk_add_f32 v[112:113], v[112:113], 1.0 op_sel_hi:[1,0]
	v_rcp_f32_e32 v130, v106
	v_rcp_f32_e32 v131, v107
	v_rcp_f32_e32 v108, v108
	v_rcp_f32_e32 v109, v109
	v_rcp_f32_e32 v110, v110
	v_rcp_f32_e32 v111, v111
	v_rcp_f32_e32 v112, v112
	v_rcp_f32_e32 v113, v113
	v_pk_add_f32 v[100:101], v[100:101], v[116:117]
	v_pk_add_f32 v[98:99], v[98:99], v[114:115]
	v_pk_add_f32 v[104:105], v[104:105], v[120:121]
	v_pk_add_f32 v[102:103], v[102:103], v[118:119]
	v_pk_mul_f32 v[108:109], v[100:101], v[108:109]
	v_pk_mul_f32 v[100:101], v[98:99], v[130:131]
	v_pk_mul_f32 v[102:103], v[102:103], v[110:111]
	v_pk_mul_f32 v[104:105], v[104:105], v[112:113]
	v_pk_mul_f32 v[98:99], v[100:101], v[100:101]
	v_pk_mul_f32 v[110:111], v[108:109], v[108:109]
	v_or_b32_e32 v106, 16, v148
	v_pk_fma_f32 v[110:111], v[104:105], v[104:105], v[110:111]
	v_pk_fma_f32 v[98:99], v[102:103], v[102:103], v[98:99]
	v_ashrrev_i32_e32 v107, 31, v106
	v_add_f32_e32 v0, v98, v99
	v_add_f32_e32 v98, v110, v111
	v_add_f32_e32 v0, v0, v98
	v_cvt_pk_bf16_f32 v98, v102, v103
	v_lshlrev_b64 v[102:103], 11, v[106:107]
	v_lshl_add_u64 v[102:103], s[10:11], 0, v[102:103]
	v_cvt_pk_bf16_f32 v99, v104, v105
	v_cvt_pk_bf16_f32 v100, v100, v101
	v_cvt_pk_bf16_f32 v101, v108, v109
	v_lshl_add_u64 v[102:103], v[146:147], 1, v[102:103]
	global_store_dwordx4 v[102:103], v[98:101], off
	s_nop 1
	v_mov_b32_e32 v98, v0
	s_nop 1
	v_permlane32_swap_b32_e32 v0, v98
	v_add_f32_e32 v0, v0, v98
	v_mov_b32_e32 v98, v0
	s_nop 1
	v_permlane16_swap_b32_e32 v0, v98
	s_and_saveexec_b64 s[60:61], vcc
	s_cbranch_execz .LBB0_1261
	v_lshlrev_b64 v[100:101], 6, v[106:107]
	v_lshl_add_u64 v[100:101], s[14:15], 0, v[100:101]
	v_lshl_add_u64 v[100:101], s[58:59], 2, v[100:101]
	s_lshl_b32 s62, s46, 2
	s_mov_b32 s63, s19
	v_lshl_add_u64 v[100:101], v[100:101], 0, s[62:63]
	v_add_f32_e32 v0, v0, v98
	global_store_dword v[100:101], v0, off sc0 sc1
; __device__ __forceinline__ u32x4 pack8(f32x4 a, f32x4 b) { u32x4 w; w.x = cvtpk(a[0], a[1]); w.y = cvtpk(a[2], a[3]); w.z = cvtpk(b[0], b[1]); w.w = cvtpk(b[2], b[3]); return w; }
; __device__ __forceinline__ float fast_exp2(float x) { return __builtin_amdgcn_exp2f(x); }
; __device__ __forceinline__ float fast_rcp(float x) { return __builtin_amdgcn_rcpf(x); }
;     __device__ __forceinline__ void operator()(AccRef acc, const Unit& u, int wr, int wc, int fr, int fq) const {
;         const int c0 = u.pn * 128 + wc * 32 + 8 * fq;
;         const f32x4 bv0 = *(const f32x4*)(bglu + c0), bv1 = *(const f32x4*)(bglu + c0 + 4), bg0 = *(const f32x4*)(bglu + 512 + c0), bg1 = *(const f32x4*)(bglu + 512 + c0 + 4);
; #pragma unroll
;         for (int ai = 0; ai < 2; ++ai)
; #pragma unroll
;             for (int m = 0; m < 4; ++m) {
;                 const int row = u.pm * 256 + ai * 128 + wr * 64 + m * 16 + fr;
;                 f32x4 o0, o1; float part = 0.f;
;                 {
;                     f32x4 g0 = (acc[ai][1][m][0] + bg0) * (-LOG2E), g1 = (acc[ai][1][m][1] + bg1) * (-LOG2E);
; #pragma unroll
;                     for (int j = 0; j < 4; ++j) { g0[j] = fast_exp2(g0[j]); g1[j] = fast_exp2(g1[j]); }
;                     g0 = g0 + 1.0f; g1 = g1 + 1.0f;
; #pragma unroll
;                     for (int j = 0; j < 4; ++j) { g0[j] = fast_rcp(g0[j]); g1[j] = fast_rcp(g1[j]); }
;                     o0 = (acc[ai][0][m][0] + bv0) * g0; o1 = (acc[ai][0][m][1] + bv1) * g1;
;                     const f32x4 sq = o0 * o0 + o1 * o1; part += (sq[0] + sq[1]) + (sq[2] + sq[3]);
;                 }
;                 *(u32x4*)(mix + (size_t)row * D + c0) = pack8(o0, o1);
;                 part = fq_sum(part);
;                 if (fq == 0) ssq[(size_t)row * 16 + u.pn * 4 + wc] = part;
;             }
.LBB0_1261:
	s_or_b64 exec, exec, s[60:61]
	v_pk_add_f32 v[92:93], v[92:93], v[124:125]
	v_pk_add_f32 v[90:91], v[90:91], v[122:123]
	v_pk_add_f32 v[96:97], v[96:97], v[128:129]
	v_pk_add_f32 v[94:95], v[94:95], v[126:127]
	v_pk_mul_f32 v[92:93], v[92:93], s[30:31] op_sel_hi:[1,0]
	v_pk_mul_f32 v[90:91], v[90:91], s[30:31] op_sel_hi:[1,0]
	v_pk_mul_f32 v[96:97], v[96:97], s[30:31] op_sel_hi:[1,0]
	v_pk_mul_f32 v[94:95], v[94:95], s[30:31] op_sel_hi:[1,0]
	v_exp_f32_e32 v90, v90
	v_exp_f32_e32 v92, v92
	v_exp_f32_e32 v93, v93
	v_exp_f32_e32 v91, v91
	v_exp_f32_e32 v94, v94
	v_exp_f32_e32 v95, v95
	v_exp_f32_e32 v96, v96
	v_exp_f32_e32 v97, v97
	v_pk_add_f32 v[92:93], v[92:93], 1.0 op_sel_hi:[1,0]
	v_pk_add_f32 v[90:91], v[90:91], 1.0 op_sel_hi:[1,0]
	v_pk_add_f32 v[94:95], v[94:95], 1.0 op_sel_hi:[1,0]
	v_pk_add_f32 v[96:97], v[96:97], 1.0 op_sel_hi:[1,0]
	v_rcp_f32_e32 v98, v90
	v_rcp_f32_e32 v99, v91
	v_rcp_f32_e32 v92, v92
	v_rcp_f32_e32 v93, v93
	v_rcp_f32_e32 v94, v94
	v_rcp_f32_e32 v95, v95
	v_rcp_f32_e32 v96, v96
	v_rcp_f32_e32 v97, v97
	v_pk_add_f32 v[84:85], v[84:85], v[116:117]
	v_pk_add_f32 v[82:83], v[82:83], v[114:115]
	v_pk_add_f32 v[88:89], v[88:89], v[120:121]
	v_pk_add_f32 v[86:87], v[86:87], v[118:119]
	v_pk_mul_f32 v[92:93], v[84:85], v[92:93]
	v_pk_mul_f32 v[84:85], v[82:83], v[98:99]
	v_pk_mul_f32 v[86:87], v[86:87], v[94:95]
	v_pk_mul_f32 v[88:89], v[88:89], v[96:97]
	v_pk_mul_f32 v[82:83], v[84:85], v[84:85]
	v_pk_mul_f32 v[94:95], v[92:93], v[92:93]
	v_or_b32_e32 v90, 32, v148
	v_pk_fma_f32 v[94:95], v[88:89], v[88:89], v[94:95]
	v_pk_fma_f32 v[82:83], v[86:87], v[86:87], v[82:83]
	v_ashrrev_i32_e32 v91, 31, v90
	v_add_f32_e32 v0, v82, v83
	v_add_f32_e32 v82, v94, v95
	v_add_f32_e32 v0, v0, v82
	v_cvt_pk_bf16_f32 v82, v86, v87
	v_lshlrev_b64 v[86:87], 11, v[90:91]
	v_lshl_add_u64 v[86:87], s[10:11], 0, v[86:87]
	v_cvt_pk_bf16_f32 v83, v88, v89
	v_cvt_pk_bf16_f32 v84, v84, v85
	v_cvt_pk_bf16_f32 v85, v92, v93
	v_lshl_add_u64 v[86:87], v[146:147], 1, v[86:87]
	global_store_dwordx4 v[86:87], v[82:85], off
	s_nop 1
	v_mov_b32_e32 v82, v0
	s_nop 1
	v_permlane32_swap_b32_e32 v0, v82
	v_add_f32_e32 v0, v0, v82
	v_mov_b32_e32 v82, v0
	s_nop 1
	v_permlane16_swap_b32_e32 v0, v82
	s_and_saveexec_b64 s[60:61], vcc
	s_cbranch_execz .LBB0_1263
	v_lshlrev_b64 v[84:85], 6, v[90:91]
	v_lshl_add_u64 v[84:85], s[14:15], 0, v[84:85]
	v_lshl_add_u64 v[84:85], s[58:59], 2, v[84:85]
	s_lshl_b32 s62, s46, 2
	s_mov_b32 s63, s19
	v_lshl_add_u64 v[84:85], v[84:85], 0, s[62:63]
	v_add_f32_e32 v0, v0, v82
	global_store_dword v[84:85], v0, off sc0 sc1
.LBB0_1263:
	s_or_b64 exec, exec, s[60:61]
	v_pk_add_f32 v[76:77], v[76:77], v[124:125]
	v_pk_add_f32 v[74:75], v[74:75], v[122:123]
	v_pk_add_f32 v[80:81], v[80:81], v[128:129]
	v_pk_add_f32 v[78:79], v[78:79], v[126:127]
	v_pk_mul_f32 v[76:77], v[76:77], s[30:31] op_sel_hi:[1,0]
	v_pk_mul_f32 v[74:75], v[74:75], s[30:31] op_sel_hi:[1,0]
	v_pk_mul_f32 v[80:81], v[80:81], s[30:31] op_sel_hi:[1,0]
	v_pk_mul_f32 v[78:79], v[78:79], s[30:31] op_sel_hi:[1,0]
	v_exp_f32_e32 v74, v74
	v_exp_f32_e32 v76, v76
	v_exp_f32_e32 v77, v77
	v_exp_f32_e32 v75, v75
	v_exp_f32_e32 v78, v78
	v_exp_f32_e32 v79, v79
	v_exp_f32_e32 v80, v80
	v_exp_f32_e32 v81, v81
	v_pk_add_f32 v[76:77], v[76:77], 1.0 op_sel_hi:[1,0]
	v_pk_add_f32 v[74:75], v[74:75], 1.0 op_sel_hi:[1,0]
	v_pk_add_f32 v[78:79], v[78:79], 1.0 op_sel_hi:[1,0]
	v_pk_add_f32 v[80:81], v[80:81], 1.0 op_sel_hi:[1,0]
	v_rcp_f32_e32 v82, v74
	v_rcp_f32_e32 v83, v75
	v_rcp_f32_e32 v76, v76
	v_rcp_f32_e32 v77, v77
	v_rcp_f32_e32 v78, v78
	v_rcp_f32_e32 v79, v79
	v_rcp_f32_e32 v80, v80
	v_rcp_f32_e32 v81, v81
	v_pk_add_f32 v[68:69], v[68:69], v[116:117]
	v_pk_add_f32 v[66:67], v[66:67], v[114:115]
	v_pk_add_f32 v[72:73], v[72:73], v[120:121]
	v_pk_add_f32 v[70:71], v[70:71], v[118:119]
	v_pk_mul_f32 v[76:77], v[68:69], v[76:77]
	v_pk_mul_f32 v[68:69], v[66:67], v[82:83]
	v_pk_mul_f32 v[70:71], v[70:71], v[78:79]
	v_pk_mul_f32 v[72:73], v[72:73], v[80:81]
	v_pk_mul_f32 v[66:67], v[68:69], v[68:69]
	v_pk_mul_f32 v[78:79], v[76:77], v[76:77]
	v_or_b32_e32 v74, 48, v148
	v_pk_fma_f32 v[78:79], v[72:73], v[72:73], v[78:79]
	v_pk_fma_f32 v[66:67], v[70:71], v[70:71], v[66:67]
	v_ashrrev_i32_e32 v75, 31, v74
	v_add_f32_e32 v0, v66, v67
	v_add_f32_e32 v66, v78, v79
	v_add_f32_e32 v0, v0, v66
	v_cvt_pk_bf16_f32 v66, v70, v71
	v_lshlrev_b64 v[70:71], 11, v[74:75]
	v_lshl_add_u64 v[70:71], s[10:11], 0, v[70:71]
	v_cvt_pk_bf16_f32 v67, v72, v73
	v_cvt_pk_bf16_f32 v68, v68, v69
	v_cvt_pk_bf16_f32 v69, v76, v77
	v_lshl_add_u64 v[70:71], v[146:147], 1, v[70:71]
	global_store_dwordx4 v[70:71], v[66:69], off
	s_nop 1
	v_mov_b32_e32 v66, v0
	s_nop 1
	v_permlane32_swap_b32_e32 v0, v66
	v_add_f32_e32 v0, v0, v66
	v_mov_b32_e32 v66, v0
	s_nop 1
	v_permlane16_swap_b32_e32 v0, v66
	s_and_saveexec_b64 s[60:61], vcc
	s_cbranch_execz .LBB0_1265
	v_lshlrev_b64 v[68:69], 6, v[74:75]
	v_lshl_add_u64 v[68:69], s[14:15], 0, v[68:69]
	v_lshl_add_u64 v[68:69], s[58:59], 2, v[68:69]
	s_lshl_b32 s62, s46, 2
	s_mov_b32 s63, s19
	v_lshl_add_u64 v[68:69], v[68:69], 0, s[62:63]
	v_add_f32_e32 v0, v0, v66
	global_store_dword v[68:69], v0, off sc0 sc1
; __device__ __forceinline__ u32x4 pack8(f32x4 a, f32x4 b) { u32x4 w; w.x = cvtpk(a[0], a[1]); w.y = cvtpk(a[2], a[3]); w.z = cvtpk(b[0], b[1]); w.w = cvtpk(b[2], b[3]); return w; }
; __device__ __forceinline__ float fast_exp2(float x) { return __builtin_amdgcn_exp2f(x); }
; __device__ __forceinline__ float fast_rcp(float x) { return __builtin_amdgcn_rcpf(x); }
;     __device__ __forceinline__ void operator()(AccRef acc, const Unit& u, int wr, int wc, int fr, int fq) const {
;         const int c0 = u.pn * 128 + wc * 32 + 8 * fq;
;         const f32x4 bv0 = *(const f32x4*)(bglu + c0), bv1 = *(const f32x4*)(bglu + c0 + 4), bg0 = *(const f32x4*)(bglu + 512 + c0), bg1 = *(const f32x4*)(bglu + 512 + c0 + 4);
; #pragma unroll
;         for (int ai = 0; ai < 2; ++ai)
; #pragma unroll
;             for (int m = 0; m < 4; ++m) {
;                 const int row = u.pm * 256 + ai * 128 + wr * 64 + m * 16 + fr;
;                 f32x4 o0, o1; float part = 0.f;
;                 {
;                     f32x4 g0 = (acc[ai][1][m][0] + bg0) * (-LOG2E), g1 = (acc[ai][1][m][1] + bg1) * (-LOG2E);
; #pragma unroll
;                     for (int j = 0; j < 4; ++j) { g0[j] = fast_exp2(g0[j]); g1[j] = fast_exp2(g1[j]); }
;                     g0 = g0 + 1.0f; g1 = g1 + 1.0f;
; #pragma unroll
;                     for (int j = 0; j < 4; ++j) { g0[j] = fast_rcp(g0[j]); g1[j] = fast_rcp(g1[j]); }
;                     o0 = (acc[ai][0][m][0] + bv0) * g0; o1 = (acc[ai][0][m][1] + bv1) * g1;
;                     const f32x4 sq = o0 * o0 + o1 * o1; part += (sq[0] + sq[1]) + (sq[2] + sq[3]);
;                 }
;                 *(u32x4*)(mix + (size_t)row * D + c0) = pack8(o0, o1);
;                 part = fq_sum(part);
;                 if (fq == 0) ssq[(size_t)row * 16 + u.pn * 4 + wc] = part;
;             }
.LBB0_1265:
	s_or_b64 exec, exec, s[60:61]
	v_pk_add_f32 v[60:61], v[60:61], v[124:125]
	v_pk_add_f32 v[58:59], v[58:59], v[122:123]
	v_pk_add_f32 v[64:65], v[64:65], v[128:129]
	v_pk_add_f32 v[62:63], v[62:63], v[126:127]
	v_pk_mul_f32 v[60:61], v[60:61], s[30:31] op_sel_hi:[1,0]
	v_pk_mul_f32 v[58:59], v[58:59], s[30:31] op_sel_hi:[1,0]
	v_pk_mul_f32 v[64:65], v[64:65], s[30:31] op_sel_hi:[1,0]
	v_pk_mul_f32 v[62:63], v[62:63], s[30:31] op_sel_hi:[1,0]
	v_exp_f32_e32 v58, v58
	v_exp_f32_e32 v60, v60
	v_exp_f32_e32 v61, v61
	v_exp_f32_e32 v59, v59
	v_exp_f32_e32 v62, v62
	v_exp_f32_e32 v63, v63
	v_exp_f32_e32 v64, v64
	v_exp_f32_e32 v65, v65
	v_pk_add_f32 v[60:61], v[60:61], 1.0 op_sel_hi:[1,0]
	v_pk_add_f32 v[58:59], v[58:59], 1.0 op_sel_hi:[1,0]
	v_pk_add_f32 v[62:63], v[62:63], 1.0 op_sel_hi:[1,0]
	v_pk_add_f32 v[64:65], v[64:65], 1.0 op_sel_hi:[1,0]
	v_rcp_f32_e32 v58, v58
	v_rcp_f32_e32 v59, v59
	v_rcp_f32_e32 v60, v60
	v_rcp_f32_e32 v61, v61
	v_rcp_f32_e32 v62, v62
	v_rcp_f32_e32 v63, v63
	v_rcp_f32_e32 v64, v64
	v_rcp_f32_e32 v65, v65
	v_pk_add_f32 v[52:53], v[52:53], v[116:117]
	v_pk_add_f32 v[50:51], v[50:51], v[114:115]
	v_pk_add_f32 v[56:57], v[56:57], v[120:121]
	v_pk_add_f32 v[54:55], v[54:55], v[118:119]
	v_pk_mul_f32 v[60:61], v[52:53], v[60:61]
	v_pk_mul_f32 v[52:53], v[50:51], v[58:59]
	v_pk_mul_f32 v[54:55], v[54:55], v[62:63]
	v_pk_mul_f32 v[56:57], v[56:57], v[64:65]
	v_pk_mul_f32 v[50:51], v[52:53], v[52:53]
	v_pk_mul_f32 v[58:59], v[60:61], v[60:61]
	v_add_u32_e32 v66, 0x80, v148
	v_pk_fma_f32 v[58:59], v[56:57], v[56:57], v[58:59]
	v_pk_fma_f32 v[50:51], v[54:55], v[54:55], v[50:51]
	v_ashrrev_i32_e32 v67, 31, v66
	v_add_f32_e32 v0, v50, v51
	v_add_f32_e32 v50, v58, v59
	v_add_f32_e32 v0, v0, v50
	v_cvt_pk_bf16_f32 v50, v54, v55
	v_lshlrev_b64 v[54:55], 11, v[66:67]
	v_lshl_add_u64 v[54:55], s[10:11], 0, v[54:55]
	v_cvt_pk_bf16_f32 v51, v56, v57
	v_cvt_pk_bf16_f32 v52, v52, v53
	v_cvt_pk_bf16_f32 v53, v60, v61
	v_lshl_add_u64 v[54:55], v[146:147], 1, v[54:55]
	global_store_dwordx4 v[54:55], v[50:53], off
	s_nop 1
	v_mov_b32_e32 v50, v0
	s_nop 1
	v_permlane32_swap_b32_e32 v0, v50
	v_add_f32_e32 v0, v0, v50
	v_mov_b32_e32 v50, v0
	s_nop 1
	v_permlane16_swap_b32_e32 v0, v50
	s_and_saveexec_b64 s[60:61], vcc
	s_cbranch_execz .LBB0_1267
	v_lshlrev_b64 v[52:53], 6, v[66:67]
	v_lshl_add_u64 v[52:53], s[14:15], 0, v[52:53]
	v_lshl_add_u64 v[52:53], s[58:59], 2, v[52:53]
	s_lshl_b32 s62, s46, 2
	s_mov_b32 s63, s19
	v_lshl_add_u64 v[52:53], v[52:53], 0, s[62:63]
	v_add_f32_e32 v0, v0, v50
	global_store_dword v[52:53], v0, off sc0 sc1
.LBB0_1267:
	s_or_b64 exec, exec, s[60:61]
	v_pk_add_f32 v[44:45], v[44:45], v[124:125]
	v_pk_add_f32 v[42:43], v[42:43], v[122:123]
	v_pk_add_f32 v[48:49], v[48:49], v[128:129]
	v_pk_add_f32 v[46:47], v[46:47], v[126:127]
	v_pk_mul_f32 v[44:45], v[44:45], s[30:31] op_sel_hi:[1,0]
	v_pk_mul_f32 v[42:43], v[42:43], s[30:31] op_sel_hi:[1,0]
	v_pk_mul_f32 v[48:49], v[48:49], s[30:31] op_sel_hi:[1,0]
	v_pk_mul_f32 v[46:47], v[46:47], s[30:31] op_sel_hi:[1,0]
	v_exp_f32_e32 v42, v42
	v_exp_f32_e32 v44, v44
	v_exp_f32_e32 v45, v45
	v_exp_f32_e32 v43, v43
	v_exp_f32_e32 v46, v46
	v_exp_f32_e32 v47, v47
	v_exp_f32_e32 v48, v48
	v_exp_f32_e32 v49, v49
	v_pk_add_f32 v[44:45], v[44:45], 1.0 op_sel_hi:[1,0]
	v_pk_add_f32 v[42:43], v[42:43], 1.0 op_sel_hi:[1,0]
	v_pk_add_f32 v[46:47], v[46:47], 1.0 op_sel_hi:[1,0]
	v_pk_add_f32 v[48:49], v[48:49], 1.0 op_sel_hi:[1,0]
	v_rcp_f32_e32 v50, v42
	v_rcp_f32_e32 v51, v43
	v_rcp_f32_e32 v44, v44
	v_rcp_f32_e32 v45, v45
	v_rcp_f32_e32 v46, v46
	v_rcp_f32_e32 v47, v47
	v_rcp_f32_e32 v48, v48
	v_rcp_f32_e32 v49, v49
	v_pk_add_f32 v[36:37], v[36:37], v[116:117]
	v_pk_add_f32 v[34:35], v[34:35], v[114:115]
	v_pk_add_f32 v[40:41], v[40:41], v[120:121]
	v_pk_add_f32 v[38:39], v[38:39], v[118:119]
	v_pk_mul_f32 v[44:45], v[36:37], v[44:45]
	v_pk_mul_f32 v[36:37], v[34:35], v[50:51]
	v_pk_mul_f32 v[38:39], v[38:39], v[46:47]
	v_pk_mul_f32 v[40:41], v[40:41], v[48:49]
	v_pk_mul_f32 v[34:35], v[36:37], v[36:37]
	v_pk_mul_f32 v[46:47], v[44:45], v[44:45]
	v_add_u32_e32 v42, 0x90, v148
	v_pk_fma_f32 v[46:47], v[40:41], v[40:41], v[46:47]
	v_pk_fma_f32 v[34:35], v[38:39], v[38:39], v[34:35]
	v_ashrrev_i32_e32 v43, 31, v42
	v_add_f32_e32 v0, v34, v35
	v_add_f32_e32 v34, v46, v47
	v_add_f32_e32 v0, v0, v34
	v_cvt_pk_bf16_f32 v34, v38, v39
	v_lshlrev_b64 v[38:39], 11, v[42:43]
	v_lshl_add_u64 v[38:39], s[10:11], 0, v[38:39]
	v_cvt_pk_bf16_f32 v35, v40, v41
	v_cvt_pk_bf16_f32 v36, v36, v37
	v_cvt_pk_bf16_f32 v37, v44, v45
	v_lshl_add_u64 v[38:39], v[146:147], 1, v[38:39]
	global_store_dwordx4 v[38:39], v[34:37], off
	s_nop 1
	v_mov_b32_e32 v34, v0
	s_nop 1
	v_permlane32_swap_b32_e32 v0, v34
	v_add_f32_e32 v0, v0, v34
	v_mov_b32_e32 v34, v0
	s_nop 1
	v_permlane16_swap_b32_e32 v0, v34
	s_and_saveexec_b64 s[60:61], vcc
	s_cbranch_execz .LBB0_1269
	v_lshlrev_b64 v[36:37], 6, v[42:43]
	v_lshl_add_u64 v[36:37], s[14:15], 0, v[36:37]
	v_lshl_add_u64 v[36:37], s[58:59], 2, v[36:37]
	s_lshl_b32 s62, s46, 2
	s_mov_b32 s63, s19
	v_lshl_add_u64 v[36:37], v[36:37], 0, s[62:63]
	v_add_f32_e32 v0, v0, v34
	global_store_dword v[36:37], v0, off sc0 sc1
; __device__ __forceinline__ u32x4 pack8(f32x4 a, f32x4 b) { u32x4 w; w.x = cvtpk(a[0], a[1]); w.y = cvtpk(a[2], a[3]); w.z = cvtpk(b[0], b[1]); w.w = cvtpk(b[2], b[3]); return w; }
; __device__ __forceinline__ float fast_exp2(float x) { return __builtin_amdgcn_exp2f(x); }
; __device__ __forceinline__ float fast_rcp(float x) { return __builtin_amdgcn_rcpf(x); }
;     __device__ __forceinline__ void operator()(AccRef acc, const Unit& u, int wr, int wc, int fr, int fq) const {
;         const int c0 = u.pn * 128 + wc * 32 + 8 * fq;
;         const f32x4 bv0 = *(const f32x4*)(bglu + c0), bv1 = *(const f32x4*)(bglu + c0 + 4), bg0 = *(const f32x4*)(bglu + 512 + c0), bg1 = *(const f32x4*)(bglu + 512 + c0 + 4);
; #pragma unroll
;         for (int ai = 0; ai < 2; ++ai)
; #pragma unroll
;             for (int m = 0; m < 4; ++m) {
;                 const int row = u.pm * 256 + ai * 128 + wr * 64 + m * 16 + fr;
;                 f32x4 o0, o1; float part = 0.f;
;                 {
;                     f32x4 g0 = (acc[ai][1][m][0] + bg0) * (-LOG2E), g1 = (acc[ai][1][m][1] + bg1) * (-LOG2E);
; #pragma unroll
;                     for (int j = 0; j < 4; ++j) { g0[j] = fast_exp2(g0[j]); g1[j] = fast_exp2(g1[j]); }
;                     g0 = g0 + 1.0f; g1 = g1 + 1.0f;
; #pragma unroll
;                     for (int j = 0; j < 4; ++j) { g0[j] = fast_rcp(g0[j]); g1[j] = fast_rcp(g1[j]); }
;                     o0 = (acc[ai][0][m][0] + bv0) * g0; o1 = (acc[ai][0][m][1] + bv1) * g1;
;                     const f32x4 sq = o0 * o0 + o1 * o1; part += (sq[0] + sq[1]) + (sq[2] + sq[3]);
;                 }
;                 *(u32x4*)(mix + (size_t)row * D + c0) = pack8(o0, o1);
;                 part = fq_sum(part);
;                 if (fq == 0) ssq[(size_t)row * 16 + u.pn * 4 + wc] = part;
;             }
.LBB0_1269:
	s_or_b64 exec, exec, s[60:61]
	v_pk_add_f32 v[28:29], v[28:29], v[124:125]
	v_pk_add_f32 v[26:27], v[26:27], v[122:123]
	v_pk_add_f32 v[32:33], v[32:33], v[128:129]
	v_pk_add_f32 v[30:31], v[30:31], v[126:127]
	v_pk_mul_f32 v[28:29], v[28:29], s[30:31] op_sel_hi:[1,0]
	v_pk_mul_f32 v[26:27], v[26:27], s[30:31] op_sel_hi:[1,0]
	v_pk_mul_f32 v[32:33], v[32:33], s[30:31] op_sel_hi:[1,0]
	v_pk_mul_f32 v[30:31], v[30:31], s[30:31] op_sel_hi:[1,0]
	v_exp_f32_e32 v26, v26
	v_exp_f32_e32 v28, v28
	v_exp_f32_e32 v29, v29
	v_exp_f32_e32 v27, v27
	v_exp_f32_e32 v30, v30
	v_exp_f32_e32 v31, v31
	v_exp_f32_e32 v32, v32
	v_exp_f32_e32 v33, v33
	v_pk_add_f32 v[28:29], v[28:29], 1.0 op_sel_hi:[1,0]
	v_pk_add_f32 v[26:27], v[26:27], 1.0 op_sel_hi:[1,0]
	v_pk_add_f32 v[30:31], v[30:31], 1.0 op_sel_hi:[1,0]
	v_pk_add_f32 v[32:33], v[32:33], 1.0 op_sel_hi:[1,0]
	v_rcp_f32_e32 v34, v26
	v_rcp_f32_e32 v35, v27
	v_rcp_f32_e32 v28, v28
	v_rcp_f32_e32 v29, v29
	v_rcp_f32_e32 v30, v30
	v_rcp_f32_e32 v31, v31
	v_rcp_f32_e32 v32, v32
	v_rcp_f32_e32 v33, v33
	v_pk_add_f32 v[20:21], v[20:21], v[116:117]
	v_pk_add_f32 v[18:19], v[18:19], v[114:115]
	v_pk_add_f32 v[24:25], v[24:25], v[120:121]
	v_pk_add_f32 v[22:23], v[22:23], v[118:119]
	v_pk_mul_f32 v[28:29], v[20:21], v[28:29]
	v_pk_mul_f32 v[20:21], v[18:19], v[34:35]
	v_pk_mul_f32 v[22:23], v[22:23], v[30:31]
	v_pk_mul_f32 v[24:25], v[24:25], v[32:33]
	v_pk_mul_f32 v[18:19], v[20:21], v[20:21]
	v_pk_mul_f32 v[30:31], v[28:29], v[28:29]
	v_add_u32_e32 v26, 0xa0, v148
	v_pk_fma_f32 v[30:31], v[24:25], v[24:25], v[30:31]
	v_pk_fma_f32 v[18:19], v[22:23], v[22:23], v[18:19]
	v_ashrrev_i32_e32 v27, 31, v26
	v_add_f32_e32 v0, v18, v19
	v_add_f32_e32 v18, v30, v31
	v_add_f32_e32 v0, v0, v18
	v_cvt_pk_bf16_f32 v18, v22, v23
	v_lshlrev_b64 v[22:23], 11, v[26:27]
	v_lshl_add_u64 v[22:23], s[10:11], 0, v[22:23]
	v_cvt_pk_bf16_f32 v19, v24, v25
	v_cvt_pk_bf16_f32 v20, v20, v21
	v_cvt_pk_bf16_f32 v21, v28, v29
	v_lshl_add_u64 v[22:23], v[146:147], 1, v[22:23]
	global_store_dwordx4 v[22:23], v[18:21], off
	s_nop 1
	v_mov_b32_e32 v18, v0
	s_nop 1
	v_permlane32_swap_b32_e32 v0, v18
	v_add_f32_e32 v0, v0, v18
	v_mov_b32_e32 v18, v0
	s_nop 1
	v_permlane16_swap_b32_e32 v0, v18
	s_and_saveexec_b64 s[60:61], vcc
	s_cbranch_execz .LBB0_1271
	v_lshlrev_b64 v[20:21], 6, v[26:27]
	v_lshl_add_u64 v[20:21], s[14:15], 0, v[20:21]
	v_lshl_add_u64 v[20:21], s[58:59], 2, v[20:21]
	s_lshl_b32 s62, s46, 2
	s_mov_b32 s63, s19
	v_lshl_add_u64 v[20:21], v[20:21], 0, s[62:63]
	v_add_f32_e32 v0, v0, v18
	global_store_dword v[20:21], v0, off sc0 sc1
.LBB0_1271:
	s_or_b64 exec, exec, s[60:61]
	v_pk_add_f32 v[8:9], v[8:9], v[124:125]
	v_pk_add_f32 v[6:7], v[6:7], v[122:123]
	v_pk_add_f32 v[16:17], v[16:17], v[128:129]
	v_pk_add_f32 v[14:15], v[14:15], v[126:127]
	v_pk_mul_f32 v[8:9], v[8:9], s[30:31] op_sel_hi:[1,0]
	v_pk_mul_f32 v[6:7], v[6:7], s[30:31] op_sel_hi:[1,0]
	v_pk_mul_f32 v[16:17], v[16:17], s[30:31] op_sel_hi:[1,0]
	v_pk_mul_f32 v[14:15], v[14:15], s[30:31] op_sel_hi:[1,0]
	v_exp_f32_e32 v6, v6
	v_exp_f32_e32 v8, v8
	v_exp_f32_e32 v9, v9
	v_exp_f32_e32 v7, v7
	v_exp_f32_e32 v14, v14
	v_exp_f32_e32 v15, v15
	v_exp_f32_e32 v16, v16
	v_exp_f32_e32 v17, v17
	v_pk_add_f32 v[8:9], v[8:9], 1.0 op_sel_hi:[1,0]
	v_pk_add_f32 v[6:7], v[6:7], 1.0 op_sel_hi:[1,0]
	v_pk_add_f32 v[14:15], v[14:15], 1.0 op_sel_hi:[1,0]
	v_pk_add_f32 v[16:17], v[16:17], 1.0 op_sel_hi:[1,0]
	v_rcp_f32_e32 v18, v6
	v_rcp_f32_e32 v19, v7
	v_rcp_f32_e32 v8, v8
	v_rcp_f32_e32 v9, v9
	v_rcp_f32_e32 v14, v14
	v_rcp_f32_e32 v15, v15
	v_rcp_f32_e32 v16, v16
	v_rcp_f32_e32 v17, v17
	v_pk_add_f32 v[4:5], v[4:5], v[116:117]
	v_pk_add_f32 v[2:3], v[2:3], v[114:115]
	v_add_u32_e32 v6, 0xb0, v148
	v_pk_add_f32 v[12:13], v[12:13], v[120:121]
	v_pk_add_f32 v[10:11], v[10:11], v[118:119]
	v_pk_mul_f32 v[8:9], v[4:5], v[8:9]
	v_pk_mul_f32 v[4:5], v[2:3], v[18:19]
	v_pk_mul_f32 v[10:11], v[10:11], v[14:15]
	v_pk_mul_f32 v[12:13], v[12:13], v[16:17]
	v_pk_mul_f32 v[2:3], v[4:5], v[4:5]
	v_pk_mul_f32 v[14:15], v[8:9], v[8:9]
	v_ashrrev_i32_e32 v7, 31, v6
	v_pk_fma_f32 v[14:15], v[12:13], v[12:13], v[14:15]
	v_pk_fma_f32 v[2:3], v[10:11], v[10:11], v[2:3]
	v_cvt_pk_bf16_f32 v4, v4, v5
	v_cvt_pk_bf16_f32 v5, v8, v9
	v_lshlrev_b64 v[8:9], 11, v[6:7]
	v_add_f32_e32 v0, v2, v3
	v_add_f32_e32 v2, v14, v15
	v_lshl_add_u64 v[8:9], s[10:11], 0, v[8:9]
	v_add_f32_e32 v0, v0, v2
	v_cvt_pk_bf16_f32 v2, v10, v11
	v_cvt_pk_bf16_f32 v3, v12, v13
	v_lshl_add_u64 v[8:9], v[146:147], 1, v[8:9]
	global_store_dwordx4 v[8:9], v[2:5], off
	s_nop 1
	v_mov_b32_e32 v2, v0
	s_nop 1
	v_permlane32_swap_b32_e32 v0, v2
	v_add_f32_e32 v0, v0, v2
	v_mov_b32_e32 v2, v0
	s_nop 1
	v_permlane16_swap_b32_e32 v0, v2
	s_and_saveexec_b64 s[60:61], vcc
	s_cbranch_execz .LBB0_1273
	v_lshlrev_b64 v[4:5], 6, v[6:7]
	v_lshl_add_u64 v[4:5], s[14:15], 0, v[4:5]
	v_lshl_add_u64 v[4:5], s[58:59], 2, v[4:5]
	s_lshl_b32 s58, s46, 2
	s_mov_b32 s59, s19
	v_lshl_add_u64 v[4:5], v[4:5], 0, s[58:59]
	v_add_f32_e32 v0, v0, v2
	global_store_dword v[4:5], v0, off sc0 sc1

; __device__ __forceinline__ unsigned xb_add(unsigned* p, unsigned v) { return __hip_atomic_fetch_add(p, v, __ATOMIC_RELAXED, __HIP_MEMORY_SCOPE_AGENT); }
; #define GSYNC() do { XcdBarrier xb_; xb_.bar = (unsigned*)(KARGS()->ws + WS_CTL) + 1024; xb_.x = xb_xcc_id(); xb_.st = (volatile LAS unsigned*)(lds + LDS_XB); xcd_barrier(xb_); } while (0)
; __device__ __forceinline__ void xcd_barrier(const XcdBarrier& b) {
;     asm volatile("s_waitcnt vmcnt(0)" ::: "memory");
;     __syncthreads();
;     if (threadIdx.x == 0) {
;         unsigned* bar = b.bar;
;         __builtin_amdgcn_s_waitcnt(0);
;         unsigned nloc = b.st[0], nx = b.st[1];
;         if (nloc == 0u) { xcd_barrier_complete(bar, b.x, nloc, nx); b.st[0] = nloc; b.st[1] = nx; }
;         const unsigned old = xb_add(&bar[XB_XSUB(b.x)], 1u);
; __global__ void __launch_bounds__(512, 2) fwd_kernel(Args a) {
;     ...
;         GSYNC();
;         { PH const float lam = smalls[l];
;           for (int rep = 0; rep < ((PROBE == 1 || ATT_VAR) ? 2 : 1); ++rep)
;           for (int uidx = bid; uidx < 512; uidx += G) { const bool var = ATT_VAR && rep == 0;
;               int bh = uidx >> 5, j = uidx & 31;
;               if (G == 256) { bh = (bid & 7) + 8 * (uidx >> 8); j = bid >> 3; }
;               const int b = bh >> 2, h = bh & 3;
;               attn_qblock(b, h, j * 128, lam, lds, (const bf16_t*)(ar + AR_Q), (const bf16_t*)(ar + AR_K), (const bf16_t*)(ar + AR_VT), (bf16_t*)(ar + AR_MIX), smalls + 16, ssm_ss + (size_t)l * T * 16, var);
.LBB0_1277:
	s_mov_b64 s[8:9], s[0:1]
	s_getreg_b32 s2, hwreg(HW_REG_XCC_ID, 0, 4)
	s_waitcnt vmcnt(0)
	s_waitcnt lgkmcnt(0)
	v_readlane_b32 s6, v255, 0
	v_readlane_b32 s7, v255, 1
	s_barrier
	s_and_saveexec_b64 s[4:5], s[6:7]
	s_cbranch_execz .Lb6a_e
	s_load_dwordx2 s[8:9], s[0:1], 0x128
	v_mov_b32_e32 v2, 0
	v_mov_b32_e32 v3, 1
	s_waitcnt lgkmcnt(0)
	s_add_u32 s8, s8, 0x7400
	s_addc_u32 s9, s9, 0
	global_atomic_add v2, v3, s[8:9]
.Lb6a_e:
	s_or_b64 exec, exec, s[4:5]
	s_mov_b32 s4, 1
	s_nop 0
	v_writelane_b32 v255, s4, 43
	v_readlane_b32 s4, v255, 8
	s_mov_b64 s[6:7], s[0:1]
	s_mov_b32 s56, s94
	s_mov_b32 s57, s4
	v_mov_b32_e32 v0, v236
	s_waitcnt lgkmcnt(0)
	s_barrier
	s_cmpk_gt_i32 s57, 0x1ff
	v_readlane_b32 s5, v255, 9
	s_cbranch_scc1 .LBB0_1383
	s_load_dwordx2 s[4:5], s[6:7], 0x128
	s_lshl_b64 s[6:7], s[48:49], 2
	v_mov_b32_e32 v0, 0x300000
	s_waitcnt lgkmcnt(0)
	s_add_u32 s6, s4, s6
	s_addc_u32 s7, s5, s7
	global_load_dword v237, v0, s[6:7]
	s_and_b32 s58, s57, 7
	s_lshr_b32 s59, s57, 3
	s_add_u32 s10, s4, 0x11000000
	s_addc_u32 s11, s5, 0
	s_add_u32 s60, s4, 0x13000000
	s_addc_u32 s61, s5, 0
	s_add_u32 s62, s4, 0x15000000
	s_addc_u32 s63, s5, 0
	s_add_u32 s12, s4, 0x19000000
	s_addc_u32 s13, s5, 0
	s_add_u32 s14, s4, 0x300040
	s_addc_u32 s15, s5, 0
	s_add_u32 s2, s4, s50
	s_addc_u32 s4, s5, s51
	v_mov_b32_e32 v0, 0x100
	s_add_u32 s16, s2, 0x1e400000
	v_cmp_eq_u32_e64 s[6:7], s56, v0
	s_addc_u32 s17, s4, 0
	s_branch .LBB0_1334

; __device__ __forceinline__ unsigned xb_ld(unsigned* p)              { return __hip_atomic_load(p, __ATOMIC_RELAXED, __HIP_MEMORY_SCOPE_AGENT); }
; #define XB_SPIN(cond, bar) do { unsigned _sp = 0; while (cond) { __builtin_amdgcn_s_sleep(1); \
;     if ((++_sp & 255u) == 0u) { if (xb_ld(&(bar)[XB_TMO])) break; if (_sp > XB_SPIN_CAP) { atomicAdd(&(bar)[XB_TMO], 1u); break; } } } } while (0)
; __device__ __forceinline__ void xcd_barrier(const XcdBarrier& b) {
;     ...
;             XB_SPIN(xb_ld(&bar[XB_XGEN(b.x)]) == gen, bar);
;             __builtin_amdgcn_fence(__ATOMIC_ACQUIRE, "agent");
; __device__ __forceinline__ void attn_qblock(int b, int h, int q0, float lam, LAS unsigned char* lds, const bf16_t* qbuf, const bf16_t* kbuf, const bf16_t* vT, bf16_t* mix, const float* bias_g, const float* ssm_sq, bool var) {
;     ...
;     ssq = fq_sum(ssq);
;     const float rn = rsqrtf(ssq * (1.f / 128.f) + EPS) * sqrtf(ss_sum16(ssm_sq, b * SEQ + qrow) * (1.f / 512.f) + EPS);
.LBB0_1333:
	v_readlane_b32 s9, v255, 43
	s_nop 1
	s_cmp_eq_u32 s9, 0
	s_cbranch_scc1 .Lb6w_done2
	v_readlane_b32 s44, v255, 0
	v_readlane_b32 s45, v255, 1
	s_nop 1
	s_and_saveexec_b64 s[46:47], s[44:45]
	s_cbranch_execz .Lb6w_e2
	s_load_dwordx2 s[44:45], s[0:1], 0x128
	v_readlane_b32 s9, v255, 10
	s_nop 1
	s_and_b32 s9, s9, 1
	s_lshl_b32 s9, s94, s9
	v_mov_b32_e32 v2, 0
	s_waitcnt lgkmcnt(0)
	s_add_u32 s44, s44, 0x7400
	s_addc_u32 s45, s45, 0
.Lb6w_p2:
	global_load_dword v3, v2, s[44:45] sc1
	s_waitcnt vmcnt(0)
	v_cmp_gt_u32_e32 vcc, s9, v3
	s_cbranch_vccz .Lb6w_d2
	s_sleep 1
	s_branch .Lb6w_p2

; __device__ __forceinline__ unsigned xb_ld(unsigned* p)              { return __hip_atomic_load(p, __ATOMIC_RELAXED, __HIP_MEMORY_SCOPE_AGENT); }
; #define XB_SPIN(cond, bar) do { unsigned _sp = 0; while (cond) { __builtin_amdgcn_s_sleep(1); \
;     if ((++_sp & 255u) == 0u) { if (xb_ld(&(bar)[XB_TMO])) break; if (_sp > XB_SPIN_CAP) { atomicAdd(&(bar)[XB_TMO], 1u); break; } } } } while (0)
; __device__ __forceinline__ void xcd_barrier(const XcdBarrier& b) {
;     ...
;             XB_SPIN(xb_ld(&bar[XB_XGEN(b.x)]) == gen, bar);
;             __builtin_amdgcn_fence(__ATOMIC_ACQUIRE, "agent");
;             asm volatile("s_waitcnt vmcnt(0)" ::: "memory");
;         }
;     }
;     __syncthreads();
.Lb6w_e2:
	s_or_b64 exec, exec, s[46:47]
	s_mov_b32 s9, 0
	s_nop 0
	v_writelane_b32 v255, s9, 43
	s_barrier
